# v62 + SSD table waves: softplus log1p(exp(v)) as ln2*log2(u) (two-term product) + (t-(u-1))/u, u=1+t (f32, about 2 ulp) instead of the 130-instruction double-float expansion on the per-chunk critical
# baseline (speedup 1.0000x reference)
; __device__ __forceinline__ void phase_ssd(const Params& p, uchar* sm, int j, bf16_t* zx, const float* dtraw, float* ssqb) {
;     ...
;                 const float v = dtr + dtb;
;                 const float dt = v > 20.f ? v : log1pf(__expf(v));
.LBB0_470:
	s_andn2_saveexec_b64 s[4:5], s[4:5]
	s_cbranch_execz .LBB0_475
	v_add_f32_e32 v106, v227, v1
	s_mov_b32 s68, 0x41a00000
	v_cmp_nlt_f32_e32 vcc, s68, v106
	s_and_saveexec_b64 s[68:69], vcc
	s_cbranch_execz .LBB0_473
	v_mul_f32_e32 v106, 0x3fb8aa3b, v106
	v_exp_f32_e32 v120, v106
	s_mov_b32 s78, 0x3f317218
	s_nop 0
	v_add_f32_e32 v108, 1.0, v120
	v_add_f32_e32 v107, -1.0, v108
	v_log_f32_e32 v109, v108
	v_rcp_f32_e32 v110, v108
	v_sub_f32_e32 v107, v120, v107
	s_nop 0
	v_mul_f32_e32 v111, 0x3f317218, v109
	v_mul_f32_e32 v107, v107, v110
	v_fma_f32 v112, v109, s78, -v111
	v_fmac_f32_e32 v112, 0xb102e308, v109
	v_add_f32_e32 v107, v107, v112
	v_add_f32_e32 v106, v111, v107
